# v47 plus stage-head flag re-test skipped on the full-tile path (branch straight to the QK block)
# baseline (speedup 1.0000x reference)
; #define LAS __attribute__((address_space(3)))
; __device__ __forceinline__ void a2_qk(const LAS unsigned char* kb, const bf16x8 (&qf)[6], const f32x16& cneg, f32x16& st0, f32x16& st1) {
;     { const bf16x8 a0 = *(const LAS bf16x8*)(kb), a1 = *(const LAS bf16x8*)(kb + 32 * AT_KROW);
;       st0 = __builtin_amdgcn_mfma_f32_32x32x16_bf16(a0, qf[0], cneg, 0, 0, 0); st1 = __builtin_amdgcn_mfma_f32_32x32x16_bf16(a1, qf[0], cneg, 0, 0, 0); }
; #pragma unroll
;     for (int s = 1; s < 6; ++s) { const bf16x8 a0 = *(const LAS bf16x8*)(kb + s * 32), a1 = *(const LAS bf16x8*)(kb + 32 * AT_KROW + s * 32);
;         st0 = __builtin_amdgcn_mfma_f32_32x32x16_bf16(a0, qf[s], st0, 0, 0, 0); st1 = __builtin_amdgcn_mfma_f32_32x32x16_bf16(a1, qf[s], st1, 0, 0, 0); }
; }
; __device__ __forceinline__ void attn2_unit(bf16_t* Z, const bf16_t* Hb, const float* rc, const float* rs, LAS unsigned char* lds, int b, int h, int qblk) {
;     ...
;         if (2 * kp + 1 <= cw) {
;             f32x16 sa0, sa1, sb0, sb1; bf16x8 pa[4], pb[4];
;             __builtin_amdgcn_s_setprio(1);
;             a2_qk(kb, qf, cneg, sa0, sa1);
;             a2_qk(kb + 64 * AT_KROW, qf, cneg, sb0, sb1);
;             __builtin_amdgcn_s_setprio(0);
;             const float mt = fmaxf(a2_max(sa0, sa1), a2_max(sb0, sb1));
;             if (kp == 0 || __builtin_amdgcn_ballot_w64(mt > 8.f) != 0ull) {
.Lattn_qk_0:
	s_setprio 1
	v_add_u32_e32 v0, v3, v156
	ds_read_b128 v[4:7], v0
	ds_read_b128 v[8:11], v0 offset:6656
	ds_read_b128 v[12:15], v0 offset:32
	ds_read_b128 v[248:251], v0 offset:6688
	v_mov_b64_e32 v[94:95], v[62:63]
	v_mov_b64_e32 v[92:93], v[60:61]
	v_mov_b64_e32 v[90:91], v[58:59]
	v_mov_b64_e32 v[88:89], v[56:57]
	v_mov_b64_e32 v[86:87], v[54:55]
	v_mov_b64_e32 v[84:85], v[52:53]
	v_mov_b64_e32 v[82:83], v[50:51]
	v_mov_b64_e32 v[80:81], v[48:49]
	s_waitcnt lgkmcnt(3)
	v_mfma_f32_32x32x16_bf16 v[112:127], v[4:7], v[128:131], v[48:63]
	ds_read_b128 v[252:255], v0 offset:64
	s_waitcnt lgkmcnt(3)
	v_mfma_f32_32x32x16_bf16 v[96:111], v[8:11], v[128:131], v[48:63]
	ds_read_b128 v[4:7], v0 offset:6720
	s_waitcnt lgkmcnt(3)
	v_mfma_f32_32x32x16_bf16 v[112:127], v[12:15], v[132:135], v[112:127]
	ds_read_b128 v[8:11], v0 offset:96
	s_waitcnt lgkmcnt(3)
	v_mfma_f32_32x32x16_bf16 v[96:111], v[248:251], v[132:135], v[96:111]
	ds_read_b128 v[12:15], v0 offset:6752
	s_waitcnt lgkmcnt(3)
	v_mfma_f32_32x32x16_bf16 v[112:127], v[252:255], v[136:139], v[112:127]
	ds_read_b128 v[248:251], v0 offset:128
	s_waitcnt lgkmcnt(3)
	v_mfma_f32_32x32x16_bf16 v[96:111], v[4:7], v[136:139], v[96:111]
	ds_read_b128 v[252:255], v0 offset:6784
	s_waitcnt lgkmcnt(3)
	v_mfma_f32_32x32x16_bf16 v[112:127], v[8:11], v[140:143], v[112:127]
	ds_read_b128 v[4:7], v0 offset:160
	s_waitcnt lgkmcnt(3)
	v_mfma_f32_32x32x16_bf16 v[96:111], v[12:15], v[140:143], v[96:111]
	ds_read_b128 v[8:11], v0 offset:13312
	s_waitcnt lgkmcnt(3)
	v_mfma_f32_32x32x16_bf16 v[112:127], v[248:251], v[144:147], v[112:127]
	ds_read_b128 v[12:15], v0 offset:6816
	s_waitcnt lgkmcnt(3)
	v_mfma_f32_32x32x16_bf16 v[96:111], v[252:255], v[144:147], v[96:111]
	ds_read_b128 v[248:251], v0 offset:19968
	s_waitcnt lgkmcnt(3)
	v_mfma_f32_32x32x16_bf16 v[112:127], v[4:7], v[148:151], v[112:127]
	ds_read_b128 v[252:255], v0 offset:13344
	s_waitcnt lgkmcnt(3)
	v_mfma_f32_32x32x16_bf16 v[64:79], v[8:11], v[128:131], v[48:63]
	ds_read_b128 v[4:7], v0 offset:20000
	s_waitcnt lgkmcnt(3)
	v_mfma_f32_32x32x16_bf16 v[96:111], v[12:15], v[148:151], v[96:111]
	ds_read_b128 v[8:11], v0 offset:13376
	s_waitcnt lgkmcnt(3)
	v_mfma_f32_32x32x16_bf16 v[80:95], v[248:251], v[128:131], v[80:95]
	ds_read_b128 v[12:15], v0 offset:20032
	s_waitcnt lgkmcnt(3)
	v_mfma_f32_32x32x16_bf16 v[64:79], v[252:255], v[132:135], v[64:79]
	ds_read_b128 v[248:251], v0 offset:13408
	s_waitcnt lgkmcnt(3)
	v_mfma_f32_32x32x16_bf16 v[80:95], v[4:7], v[132:135], v[80:95]
	ds_read_b128 v[252:255], v0 offset:20064
	s_waitcnt lgkmcnt(3)
	v_mfma_f32_32x32x16_bf16 v[64:79], v[8:11], v[136:139], v[64:79]
	ds_read_b128 v[4:7], v0 offset:13440
	s_waitcnt lgkmcnt(3)
	v_mfma_f32_32x32x16_bf16 v[80:95], v[12:15], v[136:139], v[80:95]
	ds_read_b128 v[8:11], v0 offset:20096
	s_waitcnt lgkmcnt(3)
	v_mfma_f32_32x32x16_bf16 v[64:79], v[248:251], v[140:143], v[64:79]
	ds_read_b128 v[12:15], v0 offset:13472
	s_waitcnt lgkmcnt(3)
	v_mfma_f32_32x32x16_bf16 v[80:95], v[252:255], v[140:143], v[80:95]
	ds_read_b128 v[248:251], v0 offset:20128
	s_waitcnt lgkmcnt(3)
	v_mfma_f32_32x32x16_bf16 v[64:79], v[4:7], v[144:147], v[64:79]
	s_waitcnt lgkmcnt(2)
	v_mfma_f32_32x32x16_bf16 v[80:95], v[8:11], v[144:147], v[80:95]
	s_waitcnt lgkmcnt(1)
	v_mfma_f32_32x32x16_bf16 v[64:79], v[12:15], v[148:151], v[64:79]
	s_waitcnt lgkmcnt(0)
	v_mfma_f32_32x32x16_bf16 v[80:95], v[248:251], v[148:151], v[80:95]
	s_nop 0
	v_max_f32_e32 v0, v96, v96
	v_max_f32_e32 v3, v112, v112
	v_max_f32_e32 v0, v3, v0
	s_nop 7
	v_max_f32_e32 v3, v80, v80
	v_max_f32_e32 v4, v64, v64
	v_max_f32_e32 v3, v4, v3
	v_max3_f32 v3, v3, v65, v81
	v_max3_f32 v3, v3, v66, v82
	v_max3_f32 v0, v0, v113, v97
	v_max3_f32 v3, v3, v67, v83
	v_max3_f32 v0, v0, v114, v98
	v_max3_f32 v3, v3, v68, v84
	v_max3_f32 v0, v0, v115, v99
	v_max3_f32 v3, v3, v69, v85
	v_max3_f32 v0, v0, v116, v100
	v_max3_f32 v3, v3, v70, v86
	v_max3_f32 v0, v0, v117, v101
	v_max3_f32 v3, v3, v71, v87
	v_max3_f32 v0, v0, v118, v102
	v_max3_f32 v3, v3, v72, v88
	v_max3_f32 v0, v0, v119, v103
	v_max3_f32 v3, v3, v73, v89
	v_max3_f32 v0, v0, v120, v104
	v_max3_f32 v3, v3, v74, v90
	v_max3_f32 v0, v0, v121, v105
	v_max3_f32 v3, v3, v75, v91
	v_max3_f32 v0, v0, v122, v106
	v_max3_f32 v3, v3, v76, v92
	v_max3_f32 v0, v0, v123, v107
	v_max3_f32 v3, v3, v77, v93
	v_max3_f32 v0, v0, v124, v108
	v_max3_f32 v3, v3, v78, v94
	v_max3_f32 v3, v3, v79, v95
	v_max3_f32 v0, v0, v125, v109
	v_max3_f32 v0, v0, v126, v110
	v_max3_f32 v0, v0, v127, v111
	s_cmp_eq_u32 s65, 1
	v_max_f32_e32 v3, v3, v0
	v_mov_b32_e32 v4, v3
	v_mov_b32_e32 v5, v3
	s_cselect_b64 s[34:35], -1, 0
	s_cmp_lg_u32 s65, 1
	v_permlane32_swap_b32_e32 v4, v5
	s_setprio 0
	v_max_f32_e32 v3, v4, v5
	s_cbranch_scc0 .LBB0_835
	v_cmp_lt_f32_e32 vcc, s53, v3
	s_mov_b64 s[24:25], 0
	s_mov_b64 s[6:7], 0
	s_cbranch_vccz .LBB0_832
	v_max_f32_e32 v0, v3, v3
	v_max_f32_e32 v0, 0, v0
	s_mov_b64 s[6:7], -1

; #define LAS __attribute__((address_space(3)))
; __device__ __forceinline__ void a2_qk(const LAS unsigned char* kb, const bf16x8 (&qf)[6], const f32x16& cneg, f32x16& st0, f32x16& st1) {
;     { const bf16x8 a0 = *(const LAS bf16x8*)(kb), a1 = *(const LAS bf16x8*)(kb + 32 * AT_KROW);
;       st0 = __builtin_amdgcn_mfma_f32_32x32x16_bf16(a0, qf[0], cneg, 0, 0, 0); st1 = __builtin_amdgcn_mfma_f32_32x32x16_bf16(a1, qf[0], cneg, 0, 0, 0); }
; #pragma unroll
;     for (int s = 1; s < 6; ++s) { const bf16x8 a0 = *(const LAS bf16x8*)(kb + s * 32), a1 = *(const LAS bf16x8*)(kb + 32 * AT_KROW + s * 32);
;         st0 = __builtin_amdgcn_mfma_f32_32x32x16_bf16(a0, qf[s], st0, 0, 0, 0); st1 = __builtin_amdgcn_mfma_f32_32x32x16_bf16(a1, qf[s], st1, 0, 0, 0); }
; }
; __device__ __forceinline__ void attn2_unit(bf16_t* Z, const bf16_t* Hb, const float* rc, const float* rs, LAS unsigned char* lds, int b, int h, int qblk) {
;     ...
;         if (2 * kp + 1 <= cw) {
;             f32x16 sa0, sa1, sb0, sb1; bf16x8 pa[4], pb[4];
;             __builtin_amdgcn_s_setprio(1);
;             a2_qk(kb, qf, cneg, sa0, sa1);
;             a2_qk(kb + 64 * AT_KROW, qf, cneg, sb0, sb1);
;             __builtin_amdgcn_s_setprio(0);
;             const float mt = fmaxf(a2_max(sa0, sa1), a2_max(sb0, sb1));
;             if (kp == 0 || __builtin_amdgcn_ballot_w64(mt > 8.f) != 0ull) {
.Lattn_qk_1:
	s_setprio 1
	v_add_u32_e32 v0, v3, v156
	ds_read_b128 v[4:7], v0
	ds_read_b128 v[8:11], v0 offset:6656
	ds_read_b128 v[12:15], v0 offset:32
	ds_read_b128 v[248:251], v0 offset:6688
	v_mov_b64_e32 v[94:95], v[62:63]
	v_mov_b64_e32 v[92:93], v[60:61]
	v_mov_b64_e32 v[90:91], v[58:59]
	v_mov_b64_e32 v[88:89], v[56:57]
	v_mov_b64_e32 v[86:87], v[54:55]
	v_mov_b64_e32 v[84:85], v[52:53]
	v_mov_b64_e32 v[82:83], v[50:51]
	v_mov_b64_e32 v[80:81], v[48:49]
	s_waitcnt lgkmcnt(3)
	v_mfma_f32_32x32x16_bf16 v[112:127], v[4:7], v[128:131], v[48:63]
	ds_read_b128 v[252:255], v0 offset:64
	s_waitcnt lgkmcnt(3)
	v_mfma_f32_32x32x16_bf16 v[96:111], v[8:11], v[128:131], v[48:63]
	ds_read_b128 v[4:7], v0 offset:6720
	s_waitcnt lgkmcnt(3)
	v_mfma_f32_32x32x16_bf16 v[112:127], v[12:15], v[132:135], v[112:127]
	ds_read_b128 v[8:11], v0 offset:96
	s_waitcnt lgkmcnt(3)
	v_mfma_f32_32x32x16_bf16 v[96:111], v[248:251], v[132:135], v[96:111]
	ds_read_b128 v[12:15], v0 offset:6752
	s_waitcnt lgkmcnt(3)
	v_mfma_f32_32x32x16_bf16 v[112:127], v[252:255], v[136:139], v[112:127]
	ds_read_b128 v[248:251], v0 offset:128
	s_waitcnt lgkmcnt(3)
	v_mfma_f32_32x32x16_bf16 v[96:111], v[4:7], v[136:139], v[96:111]
	ds_read_b128 v[252:255], v0 offset:6784
	s_waitcnt lgkmcnt(3)
	v_mfma_f32_32x32x16_bf16 v[112:127], v[8:11], v[140:143], v[112:127]
	ds_read_b128 v[4:7], v0 offset:160
	s_waitcnt lgkmcnt(3)
	v_mfma_f32_32x32x16_bf16 v[96:111], v[12:15], v[140:143], v[96:111]
	ds_read_b128 v[8:11], v0 offset:13312
	s_waitcnt lgkmcnt(3)
	v_mfma_f32_32x32x16_bf16 v[112:127], v[248:251], v[144:147], v[112:127]
	ds_read_b128 v[12:15], v0 offset:6816
	s_waitcnt lgkmcnt(3)
	v_mfma_f32_32x32x16_bf16 v[96:111], v[252:255], v[144:147], v[96:111]
	ds_read_b128 v[248:251], v0 offset:19968
	s_waitcnt lgkmcnt(3)
	v_mfma_f32_32x32x16_bf16 v[112:127], v[4:7], v[148:151], v[112:127]
	ds_read_b128 v[252:255], v0 offset:13344
	s_waitcnt lgkmcnt(3)
	v_mfma_f32_32x32x16_bf16 v[64:79], v[8:11], v[128:131], v[48:63]
	ds_read_b128 v[4:7], v0 offset:20000
	s_waitcnt lgkmcnt(3)
	v_mfma_f32_32x32x16_bf16 v[96:111], v[12:15], v[148:151], v[96:111]
	ds_read_b128 v[8:11], v0 offset:13376
	s_waitcnt lgkmcnt(3)
	v_mfma_f32_32x32x16_bf16 v[80:95], v[248:251], v[128:131], v[80:95]
	ds_read_b128 v[12:15], v0 offset:20032
	s_waitcnt lgkmcnt(3)
	v_mfma_f32_32x32x16_bf16 v[64:79], v[252:255], v[132:135], v[64:79]
	ds_read_b128 v[248:251], v0 offset:13408
	s_waitcnt lgkmcnt(3)
	v_mfma_f32_32x32x16_bf16 v[80:95], v[4:7], v[132:135], v[80:95]
	ds_read_b128 v[252:255], v0 offset:20064
	s_waitcnt lgkmcnt(3)
	v_mfma_f32_32x32x16_bf16 v[64:79], v[8:11], v[136:139], v[64:79]
	ds_read_b128 v[4:7], v0 offset:13440
	s_waitcnt lgkmcnt(3)
	v_mfma_f32_32x32x16_bf16 v[80:95], v[12:15], v[136:139], v[80:95]
	ds_read_b128 v[8:11], v0 offset:20096
	s_waitcnt lgkmcnt(3)
	v_mfma_f32_32x32x16_bf16 v[64:79], v[248:251], v[140:143], v[64:79]
	ds_read_b128 v[12:15], v0 offset:13472
	s_waitcnt lgkmcnt(3)
	v_mfma_f32_32x32x16_bf16 v[80:95], v[252:255], v[140:143], v[80:95]
	ds_read_b128 v[248:251], v0 offset:20128
	s_waitcnt lgkmcnt(3)
	v_mfma_f32_32x32x16_bf16 v[64:79], v[4:7], v[144:147], v[64:79]
	s_waitcnt lgkmcnt(2)
	v_mfma_f32_32x32x16_bf16 v[80:95], v[8:11], v[144:147], v[80:95]
	s_waitcnt lgkmcnt(1)
	v_mfma_f32_32x32x16_bf16 v[64:79], v[12:15], v[148:151], v[64:79]
	s_waitcnt lgkmcnt(0)
	v_mfma_f32_32x32x16_bf16 v[80:95], v[248:251], v[148:151], v[80:95]
	s_nop 0
	v_max_f32_e32 v0, v96, v96
	v_max_f32_e32 v3, v112, v112
	v_max_f32_e32 v0, v3, v0
	s_nop 7
	v_max_f32_e32 v3, v80, v80
	v_max_f32_e32 v4, v64, v64
	v_max_f32_e32 v3, v4, v3
	v_max3_f32 v3, v3, v65, v81
	v_max3_f32 v3, v3, v66, v82
	v_max3_f32 v0, v0, v113, v97
	v_max3_f32 v3, v3, v67, v83
	v_max3_f32 v0, v0, v114, v98
	v_max3_f32 v3, v3, v68, v84
	v_max3_f32 v0, v0, v115, v99
	v_max3_f32 v3, v3, v69, v85
	v_max3_f32 v0, v0, v116, v100
	v_max3_f32 v3, v3, v70, v86
	v_max3_f32 v0, v0, v117, v101
	v_max3_f32 v3, v3, v71, v87
	v_max3_f32 v0, v0, v118, v102
	v_max3_f32 v3, v3, v72, v88
	v_max3_f32 v0, v0, v119, v103
	v_max3_f32 v3, v3, v73, v89
	v_max3_f32 v0, v0, v120, v104
	v_max3_f32 v3, v3, v74, v90
	v_max3_f32 v0, v0, v121, v105
	v_max3_f32 v3, v3, v75, v91
	v_max3_f32 v0, v0, v122, v106
	v_max3_f32 v3, v3, v76, v92
	v_max3_f32 v0, v0, v123, v107
	v_max3_f32 v3, v3, v77, v93
	v_max3_f32 v0, v0, v124, v108
	v_max3_f32 v3, v3, v78, v94
	v_max3_f32 v3, v3, v79, v95
	v_max3_f32 v0, v0, v125, v109
	v_max3_f32 v0, v0, v126, v110
	v_max3_f32 v0, v0, v127, v111
	s_cmp_eq_u32 s35, 1
	v_max_f32_e32 v3, v3, v0
	v_mov_b32_e32 v4, v3
	v_mov_b32_e32 v5, v3
	s_cselect_b64 s[28:29], -1, 0
	s_cmp_lg_u32 s35, 1
	v_permlane32_swap_b32_e32 v4, v5
	s_setprio 0
	v_max_f32_e32 v3, v4, v5
	s_cbranch_scc0 .LBB0_881
	v_cmp_lt_f32_e32 vcc, s53, v3
	s_mov_b64 s[24:25], 0
	s_mov_b64 s[6:7], 0
	s_cbranch_vccz .LBB0_878
	v_max_f32_e32 v0, v3, v3
	v_max_f32_e32 v0, 0, v0
	s_mov_b64 s[6:7], -1

; #define LAS __attribute__((address_space(3)))
; __device__ __forceinline__ void a2_qk(const LAS unsigned char* kb, const bf16x8 (&qf)[6], const f32x16& cneg, f32x16& st0, f32x16& st1) {
;     { const bf16x8 a0 = *(const LAS bf16x8*)(kb), a1 = *(const LAS bf16x8*)(kb + 32 * AT_KROW);
;       st0 = __builtin_amdgcn_mfma_f32_32x32x16_bf16(a0, qf[0], cneg, 0, 0, 0); st1 = __builtin_amdgcn_mfma_f32_32x32x16_bf16(a1, qf[0], cneg, 0, 0, 0); }
; #pragma unroll
;     for (int s = 1; s < 6; ++s) { const bf16x8 a0 = *(const LAS bf16x8*)(kb + s * 32), a1 = *(const LAS bf16x8*)(kb + 32 * AT_KROW + s * 32);
;         st0 = __builtin_amdgcn_mfma_f32_32x32x16_bf16(a0, qf[s], st0, 0, 0, 0); st1 = __builtin_amdgcn_mfma_f32_32x32x16_bf16(a1, qf[s], st1, 0, 0, 0); }
; }
; __device__ __forceinline__ float a2_max(const f32x16& st0, const f32x16& st1) {
;     float mt = fmaxf(st0[0], st1[0]);
; #pragma unroll
;     for (int r = 1; r < 16; ++r) mt = fmaxf(fmaxf(mt, st0[r]), st1[r]);
;     return fmaxf(mt, __shfl_xor(mt, 32));
; }
.Lattn_qk_2:
	s_setprio 1
	v_add_u32_e32 v0, v3, v156
	ds_read_b128 v[4:7], v0
	ds_read_b128 v[8:11], v0 offset:6656
	ds_read_b128 v[12:15], v0 offset:32
	ds_read_b128 v[248:251], v0 offset:6688
	v_mov_b64_e32 v[94:95], v[62:63]
	v_mov_b64_e32 v[92:93], v[60:61]
	v_mov_b64_e32 v[90:91], v[58:59]
	v_mov_b64_e32 v[88:89], v[56:57]
	v_mov_b64_e32 v[86:87], v[54:55]
	v_mov_b64_e32 v[84:85], v[52:53]
	v_mov_b64_e32 v[82:83], v[50:51]
	v_mov_b64_e32 v[80:81], v[48:49]
	s_waitcnt lgkmcnt(3)
	v_mfma_f32_32x32x16_bf16 v[112:127], v[4:7], v[128:131], v[48:63]
	ds_read_b128 v[252:255], v0 offset:64
	s_waitcnt lgkmcnt(3)
	v_mfma_f32_32x32x16_bf16 v[96:111], v[8:11], v[128:131], v[48:63]
	ds_read_b128 v[4:7], v0 offset:6720
	s_waitcnt lgkmcnt(3)
	v_mfma_f32_32x32x16_bf16 v[112:127], v[12:15], v[132:135], v[112:127]
	ds_read_b128 v[8:11], v0 offset:96
	s_waitcnt lgkmcnt(3)
	v_mfma_f32_32x32x16_bf16 v[96:111], v[248:251], v[132:135], v[96:111]
	ds_read_b128 v[12:15], v0 offset:6752
	s_waitcnt lgkmcnt(3)
	v_mfma_f32_32x32x16_bf16 v[112:127], v[252:255], v[136:139], v[112:127]
	ds_read_b128 v[248:251], v0 offset:128
	s_waitcnt lgkmcnt(3)
	v_mfma_f32_32x32x16_bf16 v[96:111], v[4:7], v[136:139], v[96:111]
	ds_read_b128 v[252:255], v0 offset:6784
	s_waitcnt lgkmcnt(3)
	v_mfma_f32_32x32x16_bf16 v[112:127], v[8:11], v[140:143], v[112:127]
	ds_read_b128 v[4:7], v0 offset:160
	s_waitcnt lgkmcnt(3)
	v_mfma_f32_32x32x16_bf16 v[96:111], v[12:15], v[140:143], v[96:111]
	ds_read_b128 v[8:11], v0 offset:13312
	s_waitcnt lgkmcnt(3)
	v_mfma_f32_32x32x16_bf16 v[112:127], v[248:251], v[144:147], v[112:127]
	ds_read_b128 v[12:15], v0 offset:6816
	s_waitcnt lgkmcnt(3)
	v_mfma_f32_32x32x16_bf16 v[96:111], v[252:255], v[144:147], v[96:111]
	ds_read_b128 v[248:251], v0 offset:19968
	s_waitcnt lgkmcnt(3)
	v_mfma_f32_32x32x16_bf16 v[112:127], v[4:7], v[148:151], v[112:127]
	ds_read_b128 v[252:255], v0 offset:13344
	s_waitcnt lgkmcnt(3)
	v_mfma_f32_32x32x16_bf16 v[64:79], v[8:11], v[128:131], v[48:63]
	ds_read_b128 v[4:7], v0 offset:20000
	s_waitcnt lgkmcnt(3)
	v_mfma_f32_32x32x16_bf16 v[96:111], v[12:15], v[148:151], v[96:111]
	ds_read_b128 v[8:11], v0 offset:13376
	s_waitcnt lgkmcnt(3)
	v_mfma_f32_32x32x16_bf16 v[80:95], v[248:251], v[128:131], v[80:95]
	ds_read_b128 v[12:15], v0 offset:20032
	s_waitcnt lgkmcnt(3)
	v_mfma_f32_32x32x16_bf16 v[64:79], v[252:255], v[132:135], v[64:79]
	ds_read_b128 v[248:251], v0 offset:13408
	s_waitcnt lgkmcnt(3)
	v_mfma_f32_32x32x16_bf16 v[80:95], v[4:7], v[132:135], v[80:95]
	ds_read_b128 v[252:255], v0 offset:20064
	s_waitcnt lgkmcnt(3)
	v_mfma_f32_32x32x16_bf16 v[64:79], v[8:11], v[136:139], v[64:79]
	ds_read_b128 v[4:7], v0 offset:13440
	s_waitcnt lgkmcnt(3)
	v_mfma_f32_32x32x16_bf16 v[80:95], v[12:15], v[136:139], v[80:95]
	ds_read_b128 v[8:11], v0 offset:20096
	s_waitcnt lgkmcnt(3)
	v_mfma_f32_32x32x16_bf16 v[64:79], v[248:251], v[140:143], v[64:79]
	ds_read_b128 v[12:15], v0 offset:13472
	s_waitcnt lgkmcnt(3)
	v_mfma_f32_32x32x16_bf16 v[80:95], v[252:255], v[140:143], v[80:95]
	ds_read_b128 v[248:251], v0 offset:20128
	s_waitcnt lgkmcnt(3)
	v_mfma_f32_32x32x16_bf16 v[64:79], v[4:7], v[144:147], v[64:79]
	s_waitcnt lgkmcnt(2)
	v_mfma_f32_32x32x16_bf16 v[80:95], v[8:11], v[144:147], v[80:95]
	s_waitcnt lgkmcnt(1)
	v_mfma_f32_32x32x16_bf16 v[64:79], v[12:15], v[148:151], v[64:79]
	s_waitcnt lgkmcnt(0)
	v_mfma_f32_32x32x16_bf16 v[80:95], v[248:251], v[148:151], v[80:95]
	s_nop 0
	v_max_f32_e32 v0, v96, v96
	v_max_f32_e32 v3, v112, v112
	v_max_f32_e32 v0, v3, v0
	s_nop 7
	v_max_f32_e32 v3, v80, v80
	v_max_f32_e32 v4, v64, v64
	v_max_f32_e32 v3, v4, v3
	v_max3_f32 v3, v3, v65, v81
	v_max3_f32 v3, v3, v66, v82
	v_max3_f32 v0, v0, v113, v97
	v_max3_f32 v3, v3, v67, v83
	v_max3_f32 v0, v0, v114, v98
	v_max3_f32 v3, v3, v68, v84
	v_max3_f32 v0, v0, v115, v99
	v_max3_f32 v3, v3, v69, v85
	v_max3_f32 v0, v0, v116, v100
	v_max3_f32 v3, v3, v70, v86
	v_max3_f32 v0, v0, v117, v101
	v_max3_f32 v3, v3, v71, v87
	v_max3_f32 v0, v0, v118, v102
	v_max3_f32 v3, v3, v72, v88
	v_max3_f32 v0, v0, v119, v103
	v_max3_f32 v3, v3, v73, v89
	v_max3_f32 v0, v0, v120, v104
	v_max3_f32 v3, v3, v74, v90
	v_max3_f32 v0, v0, v121, v105
	v_max3_f32 v3, v3, v75, v91
	v_max3_f32 v0, v0, v122, v106
	v_max3_f32 v3, v3, v76, v92
	v_max3_f32 v0, v0, v123, v107
	v_max3_f32 v3, v3, v77, v93
	v_max3_f32 v0, v0, v124, v108
	v_max3_f32 v3, v3, v78, v94
	v_max3_f32 v3, v3, v79, v95
	v_max3_f32 v0, v0, v125, v109
	v_max3_f32 v0, v0, v126, v110
	v_max3_f32 v0, v0, v127, v111
	s_cmp_eq_u32 s47, 1
	v_max_f32_e32 v3, v3, v0
	v_mov_b32_e32 v4, v3
	v_mov_b32_e32 v5, v3
	s_cselect_b64 s[30:31], -1, 0
	s_cmp_lg_u32 s47, 1
	v_permlane32_swap_b32_e32 v4, v5
	s_setprio 0
	v_max_f32_e32 v3, v4, v5
	s_cbranch_scc0 .LBB0_2246
	v_cmp_lt_f32_e32 vcc, s41, v3
	s_mov_b64 s[24:25], 0
	s_mov_b64 s[6:7], 0
	s_cbranch_vccz .LBB0_2243
	v_max_f32_e32 v0, v3, v3
	v_max_f32_e32 v0, 0, v0
	s_mov_b64 s[6:7], -1

; #define LAS __attribute__((address_space(3)))
; __device__ __forceinline__ void a2_qk(const LAS unsigned char* kb, const bf16x8 (&qf)[6], const f32x16& cneg, f32x16& st0, f32x16& st1) {
;     { const bf16x8 a0 = *(const LAS bf16x8*)(kb), a1 = *(const LAS bf16x8*)(kb + 32 * AT_KROW);
;       st0 = __builtin_amdgcn_mfma_f32_32x32x16_bf16(a0, qf[0], cneg, 0, 0, 0); st1 = __builtin_amdgcn_mfma_f32_32x32x16_bf16(a1, qf[0], cneg, 0, 0, 0); }
; #pragma unroll
;     for (int s = 1; s < 6; ++s) { const bf16x8 a0 = *(const LAS bf16x8*)(kb + s * 32), a1 = *(const LAS bf16x8*)(kb + 32 * AT_KROW + s * 32);
;         st0 = __builtin_amdgcn_mfma_f32_32x32x16_bf16(a0, qf[s], st0, 0, 0, 0); st1 = __builtin_amdgcn_mfma_f32_32x32x16_bf16(a1, qf[s], st1, 0, 0, 0); }
; }
; __device__ __forceinline__ float a2_max(const f32x16& st0, const f32x16& st1) {
;     float mt = fmaxf(st0[0], st1[0]);
; #pragma unroll
;     for (int r = 1; r < 16; ++r) mt = fmaxf(fmaxf(mt, st0[r]), st1[r]);
;     return fmaxf(mt, __shfl_xor(mt, 32));
; }
.Lattn_qk_3:
	s_setprio 1
	v_add_u32_e32 v0, v3, v156
	ds_read_b128 v[4:7], v0
	ds_read_b128 v[8:11], v0 offset:6656
	ds_read_b128 v[12:15], v0 offset:32
	ds_read_b128 v[248:251], v0 offset:6688
	v_mov_b64_e32 v[94:95], v[62:63]
	v_mov_b64_e32 v[92:93], v[60:61]
	v_mov_b64_e32 v[90:91], v[58:59]
	v_mov_b64_e32 v[88:89], v[56:57]
	v_mov_b64_e32 v[86:87], v[54:55]
	v_mov_b64_e32 v[84:85], v[52:53]
	v_mov_b64_e32 v[82:83], v[50:51]
	v_mov_b64_e32 v[80:81], v[48:49]
	s_waitcnt lgkmcnt(3)
	v_mfma_f32_32x32x16_bf16 v[112:127], v[4:7], v[128:131], v[48:63]
	ds_read_b128 v[252:255], v0 offset:64
	s_waitcnt lgkmcnt(3)
	v_mfma_f32_32x32x16_bf16 v[96:111], v[8:11], v[128:131], v[48:63]
	ds_read_b128 v[4:7], v0 offset:6720
	s_waitcnt lgkmcnt(3)
	v_mfma_f32_32x32x16_bf16 v[112:127], v[12:15], v[132:135], v[112:127]
	ds_read_b128 v[8:11], v0 offset:96
	s_waitcnt lgkmcnt(3)
	v_mfma_f32_32x32x16_bf16 v[96:111], v[248:251], v[132:135], v[96:111]
	ds_read_b128 v[12:15], v0 offset:6752
	s_waitcnt lgkmcnt(3)
	v_mfma_f32_32x32x16_bf16 v[112:127], v[252:255], v[136:139], v[112:127]
	ds_read_b128 v[248:251], v0 offset:128
	s_waitcnt lgkmcnt(3)
	v_mfma_f32_32x32x16_bf16 v[96:111], v[4:7], v[136:139], v[96:111]
	ds_read_b128 v[252:255], v0 offset:6784
	s_waitcnt lgkmcnt(3)
	v_mfma_f32_32x32x16_bf16 v[112:127], v[8:11], v[140:143], v[112:127]
	ds_read_b128 v[4:7], v0 offset:160
	s_waitcnt lgkmcnt(3)
	v_mfma_f32_32x32x16_bf16 v[96:111], v[12:15], v[140:143], v[96:111]
	ds_read_b128 v[8:11], v0 offset:13312
	s_waitcnt lgkmcnt(3)
	v_mfma_f32_32x32x16_bf16 v[112:127], v[248:251], v[144:147], v[112:127]
	ds_read_b128 v[12:15], v0 offset:6816
	s_waitcnt lgkmcnt(3)
	v_mfma_f32_32x32x16_bf16 v[96:111], v[252:255], v[144:147], v[96:111]
	ds_read_b128 v[248:251], v0 offset:19968
	s_waitcnt lgkmcnt(3)
	v_mfma_f32_32x32x16_bf16 v[112:127], v[4:7], v[148:151], v[112:127]
	ds_read_b128 v[252:255], v0 offset:13344
	s_waitcnt lgkmcnt(3)
	v_mfma_f32_32x32x16_bf16 v[64:79], v[8:11], v[128:131], v[48:63]
	ds_read_b128 v[4:7], v0 offset:20000
	s_waitcnt lgkmcnt(3)
	v_mfma_f32_32x32x16_bf16 v[96:111], v[12:15], v[148:151], v[96:111]
	ds_read_b128 v[8:11], v0 offset:13376
	s_waitcnt lgkmcnt(3)
	v_mfma_f32_32x32x16_bf16 v[80:95], v[248:251], v[128:131], v[80:95]
	ds_read_b128 v[12:15], v0 offset:20032
	s_waitcnt lgkmcnt(3)
	v_mfma_f32_32x32x16_bf16 v[64:79], v[252:255], v[132:135], v[64:79]
	ds_read_b128 v[248:251], v0 offset:13408
	s_waitcnt lgkmcnt(3)
	v_mfma_f32_32x32x16_bf16 v[80:95], v[4:7], v[132:135], v[80:95]
	ds_read_b128 v[252:255], v0 offset:20064
	s_waitcnt lgkmcnt(3)
	v_mfma_f32_32x32x16_bf16 v[64:79], v[8:11], v[136:139], v[64:79]
	ds_read_b128 v[4:7], v0 offset:13440
	s_waitcnt lgkmcnt(3)
	v_mfma_f32_32x32x16_bf16 v[80:95], v[12:15], v[136:139], v[80:95]
	ds_read_b128 v[8:11], v0 offset:20096
	s_waitcnt lgkmcnt(3)
	v_mfma_f32_32x32x16_bf16 v[64:79], v[248:251], v[140:143], v[64:79]
	ds_read_b128 v[12:15], v0 offset:13472
	s_waitcnt lgkmcnt(3)
	v_mfma_f32_32x32x16_bf16 v[80:95], v[252:255], v[140:143], v[80:95]
	ds_read_b128 v[248:251], v0 offset:20128
	s_waitcnt lgkmcnt(3)
	v_mfma_f32_32x32x16_bf16 v[64:79], v[4:7], v[144:147], v[64:79]
	s_waitcnt lgkmcnt(2)
	v_mfma_f32_32x32x16_bf16 v[80:95], v[8:11], v[144:147], v[80:95]
	s_waitcnt lgkmcnt(1)
	v_mfma_f32_32x32x16_bf16 v[64:79], v[12:15], v[148:151], v[64:79]
	s_waitcnt lgkmcnt(0)
	v_mfma_f32_32x32x16_bf16 v[80:95], v[248:251], v[148:151], v[80:95]
	s_nop 0
	v_max_f32_e32 v0, v96, v96
	v_max_f32_e32 v3, v112, v112
	v_max_f32_e32 v0, v3, v0
	s_nop 7
	v_max_f32_e32 v3, v80, v80
	v_max_f32_e32 v4, v64, v64
	v_max_f32_e32 v3, v4, v3
	v_max3_f32 v3, v3, v65, v81
	v_max3_f32 v3, v3, v66, v82
	v_max3_f32 v0, v0, v113, v97
	v_max3_f32 v3, v3, v67, v83
	v_max3_f32 v0, v0, v114, v98
	v_max3_f32 v3, v3, v68, v84
	v_max3_f32 v0, v0, v115, v99
	v_max3_f32 v3, v3, v69, v85
	v_max3_f32 v0, v0, v116, v100
	v_max3_f32 v3, v3, v70, v86
	v_max3_f32 v0, v0, v117, v101
	v_max3_f32 v3, v3, v71, v87
	v_max3_f32 v0, v0, v118, v102
	v_max3_f32 v3, v3, v72, v88
	v_max3_f32 v0, v0, v119, v103
	v_max3_f32 v3, v3, v73, v89
	v_max3_f32 v0, v0, v120, v104
	v_max3_f32 v3, v3, v74, v90
	v_max3_f32 v0, v0, v121, v105
	v_max3_f32 v3, v3, v75, v91
	v_max3_f32 v0, v0, v122, v106
	v_max3_f32 v3, v3, v76, v92
	v_max3_f32 v0, v0, v123, v107
	v_max3_f32 v3, v3, v77, v93
	v_max3_f32 v0, v0, v124, v108
	v_max3_f32 v3, v3, v78, v94
	v_max3_f32 v3, v3, v79, v95
	v_max3_f32 v0, v0, v125, v109
	v_max3_f32 v0, v0, v126, v110
	v_max3_f32 v0, v0, v127, v111
	s_cmp_eq_u32 s31, 1
	v_max_f32_e32 v3, v3, v0
	v_mov_b32_e32 v4, v3
	v_mov_b32_e32 v5, v3
	s_cselect_b64 s[26:27], -1, 0
	s_cmp_lg_u32 s31, 1
	v_permlane32_swap_b32_e32 v4, v5
	s_setprio 0
	v_max_f32_e32 v3, v4, v5
	s_cbranch_scc0 .LBB0_2292
	v_cmp_lt_f32_e32 vcc, s41, v3
	s_mov_b64 s[24:25], 0
	s_mov_b64 s[6:7], 0
	s_cbranch_vccz .LBB0_2289
	v_max_f32_e32 v0, v3, v3
	v_max_f32_e32 v0, 0, v0
	s_mov_b64 s[6:7], -1
